# prologue fourier fold: w_in block staged to LDS with eight back-to-back coalesced loads per thread (one round trip, scalar base stepping) instead of two serialized batches with heavy address arithmeti
# speedup vs baseline: 1.0038x; 1.0038x over previous
.LBB0_43:
	s_ashr_i32 s10, s9, 31
	s_lshr_b32 s11, s10, 24
	s_add_i32 s11, s9, s11
	s_lshr_b32 s10, s10, 26
	s_ashr_i32 s24, s11, 8
	s_add_i32 s11, s9, s10
	s_ashr_i32 s10, s11, 6
	s_lshr_b32 s12, s10, 30
	s_add_i32 s12, s10, s12
	s_and_b32 s12, s12, -4
	s_andn2_b32 s11, s11, 63
	s_sub_i32 s10, s10, s12
	s_sub_i32 s11, s9, s11
	s_and_saveexec_b64 s[26:27], s[40:41]
	s_cbranch_execz .LBB0_55
	s_load_dwordx2 s[28:29], s[22:23], 0x40
	s_lshl_b32 s12, s11, 5
	s_lshl_b32 s13, s24, 11
	s_add_i32 s12, s12, s13
	s_lshl_b32 s34, s10, 7
	s_addk_i32 s34, 0x600
	v_lshrrev_b32_e32 v4, 7, v26
	v_and_b32_e32 v5, 0x7f, v26
	v_add_u32_e32 v6, s12, v4
	v_mul_u32_u24_e32 v6, 0x1200, v6
	v_add3_u32 v6, v6, s34, v5
	v_lshlrev_b32_e32 v6, 2, v6
	v_mul_u32_u24_e32 v7, 0x90, v5
	v_lshl_add_u32 v7, v4, 2, v7
	s_waitcnt lgkmcnt(0)
	s_mov_b64 s[52:53], s[28:29]
	global_load_dword v8, v6, s[52:53]
	s_add_u32 s52, s52, 0x12000
	s_addc_u32 s53, s53, 0
	global_load_dword v9, v6, s[52:53]
	s_add_u32 s52, s52, 0x12000
	s_addc_u32 s53, s53, 0
	global_load_dword v10, v6, s[52:53]
	s_add_u32 s52, s52, 0x12000
	s_addc_u32 s53, s53, 0
	global_load_dword v11, v6, s[52:53]
	s_add_u32 s52, s52, 0x12000
	s_addc_u32 s53, s53, 0
	global_load_dword v12, v6, s[52:53]
	s_add_u32 s52, s52, 0x12000
	s_addc_u32 s53, s53, 0
	global_load_dword v13, v6, s[52:53]
	s_add_u32 s52, s52, 0x12000
	s_addc_u32 s53, s53, 0
	global_load_dword v14, v6, s[52:53]
	s_add_u32 s52, s52, 0x12000
	s_addc_u32 s53, s53, 0
	global_load_dword v15, v6, s[52:53]
	s_waitcnt vmcnt(0)
	ds_write_b32 v7, v8 offset:1024
	ds_write_b32 v7, v9 offset:1040
	ds_write_b32 v7, v10 offset:1056
	ds_write_b32 v7, v11 offset:1072
	ds_write_b32 v7, v12 offset:1088
	ds_write_b32 v7, v13 offset:1104
	ds_write_b32 v7, v14 offset:1120
	ds_write_b32 v7, v15 offset:1136
